# XCD-local seams as a flag barrier (plain per-workgroup generation store + L1-bypassing poll of the class's 128-byte line), L1 invalidate issued at arrival
# speedup vs baseline: 1.0226x; 1.0148x over previous
; #define LAS __attribute__((address_space(3)))
; #define TID0() (wave0 * 64 + hw_lane())
; __global__ void __launch_bounds__(512) fwd_kernel(Args a) {
;     extern __shared__ __attribute__((aligned(16))) unsigned char lds_raw[];
;     cg::grid_group grid = cg::this_grid();
;     LAS unsigned char* lds = (LAS unsigned char*)lds_raw;
;     const int wave0 = __builtin_amdgcn_readfirstlane(threadIdx.x >> 6), G = gridDim.x;
;     ...
;     const int lo = a.ph_lo, hi = a.ph_hi;
;     if (hi > 1000) grid.sync();
;     volatile LAS unsigned* bst = (volatile LAS unsigned*)(lds + 131072);
;     if (TID0() < 16) bst[TID0()] = 0u;
;     __syncthreads();
;     XcdBarrier bar = xcd_barrier_post((unsigned*)(a.ws + WS_BAR), bst);
_Z10fwd_kernel4Args:
	s_mov_b32 s100, 0
	v_writelane_b32 v255, s100, 41
	v_writelane_b32 v255, s100, 42
	s_mov_b32 s101, 0
	s_load_dwordx8 s[76:83], s[0:1], 0x80
	s_load_dword s3, s[0:1], 0xa8
	s_load_dwordx2 s[88:89], s[0:1], 0xa0
	s_add_u32 s6, s0, 0xa0
	s_addc_u32 s7, s1, 0
	v_and_b32_e32 v1, 0x3ff, v0
	s_mov_b32 s66, s2
	s_movk_i32 s4, 0x3ff
	s_waitcnt lgkmcnt(0)
	s_cmpk_lt_i32 s83, 0x3e9
	v_readfirstlane_b32 s2, v1
	s_cbranch_scc1 .LBB0_12
	v_lshrrev_b32_e32 v2, 20, v0
	v_lshrrev_b32_e32 v0, 10, v0
	v_or_b32_e32 v0, v0, v2
	v_and_or_b32 v0, v0, s4, v1
	v_cmp_eq_u32_e32 vcc, 0, v0
	s_barrier
	s_and_saveexec_b64 s[4:5], vcc
	s_cbranch_execz .LBB0_11
	buffer_wbl2 sc1
	s_load_dwordx2 s[6:7], s[6:7], 0x58
	s_mov_b64 s[8:9], exec
	v_mbcnt_lo_u32_b32 v0, s8, 0
	v_mbcnt_hi_u32_b32 v0, s9, v0
	v_cmp_eq_u32_e32 vcc, 0, v0
	s_waitcnt lgkmcnt(0)
	s_load_dword s12, s[6:7], 0x28
	s_and_saveexec_b64 s[10:11], vcc
	s_cbranch_execz .LBB0_4
	s_bcnt1_i32_b64 s8, s[8:9]
	v_mov_b32_e32 v2, 0
	v_mov_b32_e32 v3, s8
	global_atomic_add v2, v2, v3, s[6:7] offset:32 sc0

; __device__ __forceinline__ unsigned xb_ld(unsigned* p)              { return __hip_atomic_load(p, __ATOMIC_RELAXED, __HIP_MEMORY_SCOPE_AGENT); }
; __device__ __forceinline__ unsigned xb_add(unsigned* p, unsigned v) { return __hip_atomic_fetch_add(p, v, __ATOMIC_RELAXED, __HIP_MEMORY_SCOPE_AGENT); }
; #define XB_SPIN(cond, bar) do { unsigned _sp = 0; while (cond) { __builtin_amdgcn_s_sleep(1); \
;     if ((++_sp & 255u) == 0u) { if (xb_ld(&(bar)[XB_TMO])) break; if (_sp > XB_SPIN_CAP) { atomicAdd(&(bar)[XB_TMO], 1u); break; } } } } while (0)
; __device__ __forceinline__ void xcd_barrier(const XcdBarrier& b) {
;     asm volatile("s_waitcnt vmcnt(0)" ::: "memory");
;     __syncthreads();
;     if (threadIdx.x == 0) {
;         unsigned* bar = b.bar;
;         __builtin_amdgcn_s_waitcnt(0);
;         unsigned nloc = b.st[0], nx = b.st[1];
;         if (nloc == 0u) { xcd_barrier_complete(bar, b.x, nloc, nx); b.st[0] = nloc; b.st[1] = nx; }
;         const unsigned old = xb_add(&bar[XB_XSUB(b.x)], 1u);
;         const unsigned gen = old / nloc;
;         if (old + 1u == (gen + 1u) * nloc) {
;             __builtin_amdgcn_fence(__ATOMIC_RELEASE, "agent");
;             asm volatile("s_waitcnt vmcnt(0)" ::: "memory");
;             const unsigned og = xb_add(&bar[XB_TOP], 1u);
;             const unsigned tg = og / nx;
;             if (og + 1u == (tg + 1u) * nx) xb_add(&bar[XB_TOPGEN], 1u);
;             else XB_SPIN(xb_ld(&bar[XB_TOPGEN]) == tg, bar);
;             __builtin_amdgcn_fence(__ATOMIC_ACQUIRE, "agent");
;             xb_add(&bar[XB_XGEN(b.x)], 1u);
;             asm volatile("s_waitcnt vmcnt(0)" ::: "memory");
;         } else {
;             XB_SPIN(xb_ld(&bar[XB_XGEN(b.x)]) == gen, bar);
;             __builtin_amdgcn_fence(__ATOMIC_ACQUIRE, "agent");
;             asm volatile("s_waitcnt vmcnt(0)" ::: "memory");
;         }
;     }
;     __syncthreads();
; }
.LBB0_202:
	v_readlane_b32 s2, v255, 26
	s_add_i32 s2, s2, 3
	s_cmp_lt_i32 s2, s83
	s_cselect_b64 s[20:21], -1, 0
	s_and_b64 s[0:1], s[0:1], s[20:21]
	s_andn2_b64 vcc, exec, s[0:1]
	s_cbranch_vccnz .LBB0_248
	v_readlane_b32 s26, v253, 1
	v_readlane_b32 s27, v253, 2
	s_waitcnt vmcnt(0)
	s_waitcnt vmcnt(0) lgkmcnt(0)
	s_barrier
	v_readlane_b32 s98, v255, 41
	s_cmp_lg_u32 s98, 0
	s_cbranch_scc0 .Lfs5_slow
	v_readlane_b32 s98, v253, 0
	s_cmp_lg_u32 s98, 0
	s_cbranch_scc1 .Lfs5_join
	v_readlane_b32 vcc_lo, v255, 42
	s_and_b32 s98, s66, 7
	s_lshl_b32 s98, s98, 7
	s_add_u32 s98, s98, 0x1783a00
	s_add_u32 s98, s80, s98
	s_addc_u32 s99, s81, 0
	s_add_i32 vcc_lo, vcc_lo, 1
	s_lshr_b32 vcc_hi, s66, 3
	s_lshl_b32 vcc_hi, vcc_hi, 2
	v_writelane_b32 v255, vcc_lo, 42
	v_mbcnt_lo_u32_b32 v5, -1, 0
	v_lshlrev_b32_e32 v5, 2, v5
	v_mov_b32_e32 v6, vcc_lo
	v_mov_b32_e32 v7, vcc_hi
	s_mov_b32 m0, 0
	s_mov_b64 exec, 1
	global_store_dword v7, v6, s[98:99]
	buffer_inv sc1
	s_mov_b32 exec_lo, -1
	s_mov_b32 exec_hi, 0
.Lfs5_poll:
	global_load_dword v4, v5, s[98:99] sc1
	s_add_i32 m0, m0, 1
	s_waitcnt vmcnt(0)
	v_cmp_ge_u32_e32 vcc, v4, v6
	s_cmp_eq_u64 vcc, exec
	s_cbranch_scc1 .Lfs5_done
	s_sleep 1
	s_cmp_lt_u32 m0, 0x20000
	s_cbranch_scc1 .Lfs5_poll
.Lfs5_done:
	s_mov_b64 exec, -1
.Lfs5_join:
	s_mov_b64 s[0:1], exec
	v_readlane_b32 s4, v253, 3
	v_readlane_b32 s5, v253, 4
	s_and_b64 s[4:5], s[0:1], s[4:5]
	s_waitcnt vmcnt(0)
	s_branch .LBB0_247
.Lfs5_slow:
	s_mov_b64 s[0:1], exec
	v_readlane_b32 s4, v253, 3
	v_readlane_b32 s5, v253, 4
	s_and_b64 s[4:5], s[0:1], s[4:5]
	s_mov_b64 exec, s[4:5]
	s_cbranch_execz .LBB0_247
	v_readlane_b32 s4, v255, 11
	s_waitcnt vmcnt(0) expcnt(0) lgkmcnt(0)
	s_nop 0
	v_mov_b32_e32 v4, s4
	ds_read_b32 v6, v4
	v_readlane_b32 s4, v255, 12
	s_waitcnt lgkmcnt(0)
	v_cmp_ne_u32_e32 vcc, 0, v6
	v_mov_b32_e32 v4, s4
	ds_read_b32 v4, v4
	s_cbranch_vccnz .LBB0_218
	s_add_u32 s30, s26, 0x1000
	s_addc_u32 s31, s27, 0
	s_add_u32 s36, s26, 0x1100
	s_addc_u32 s37, s27, 0
	s_add_u32 s38, s26, 0x1200
	s_addc_u32 s39, s27, 0
	s_add_u32 s40, s26, 0x1300
	s_addc_u32 s41, s27, 0
	s_mov_b32 s4, 1
	s_mov_b64 s[42:43], 0
	s_branch .LBB0_208

; __device__ __forceinline__ unsigned xb_ld(unsigned* p)              { return __hip_atomic_load(p, __ATOMIC_RELAXED, __HIP_MEMORY_SCOPE_AGENT); }
; __device__ __forceinline__ unsigned xb_add(unsigned* p, unsigned v) { return __hip_atomic_fetch_add(p, v, __ATOMIC_RELAXED, __HIP_MEMORY_SCOPE_AGENT); }
; #define XB_SPIN(cond, bar) do { unsigned _sp = 0; while (cond) { __builtin_amdgcn_s_sleep(1); \
;     if ((++_sp & 255u) == 0u) { if (xb_ld(&(bar)[XB_TMO])) break; if (_sp > XB_SPIN_CAP) { atomicAdd(&(bar)[XB_TMO], 1u); break; } } } } while (0)
; __device__ __forceinline__ void xcd_barrier(const XcdBarrier& b) {
;     asm volatile("s_waitcnt vmcnt(0)" ::: "memory");
;     __syncthreads();
;     if (threadIdx.x == 0) {
;         unsigned* bar = b.bar;
;         __builtin_amdgcn_s_waitcnt(0);
;         unsigned nloc = b.st[0], nx = b.st[1];
;         if (nloc == 0u) { xcd_barrier_complete(bar, b.x, nloc, nx); b.st[0] = nloc; b.st[1] = nx; }
;         const unsigned old = xb_add(&bar[XB_XSUB(b.x)], 1u);
;         const unsigned gen = old / nloc;
;         if (old + 1u == (gen + 1u) * nloc) {
;             __builtin_amdgcn_fence(__ATOMIC_RELEASE, "agent");
;             asm volatile("s_waitcnt vmcnt(0)" ::: "memory");
;             const unsigned og = xb_add(&bar[XB_TOP], 1u);
;             const unsigned tg = og / nx;
;             if (og + 1u == (tg + 1u) * nx) xb_add(&bar[XB_TOPGEN], 1u);
;             else XB_SPIN(xb_ld(&bar[XB_TOPGEN]) == tg, bar);
;             __builtin_amdgcn_fence(__ATOMIC_ACQUIRE, "agent");
;             xb_add(&bar[XB_XGEN(b.x)], 1u);
;             asm volatile("s_waitcnt vmcnt(0)" ::: "memory");
;         } else {
;             XB_SPIN(xb_ld(&bar[XB_XGEN(b.x)]) == gen, bar);
;             __builtin_amdgcn_fence(__ATOMIC_ACQUIRE, "agent");
;             asm volatile("s_waitcnt vmcnt(0)" ::: "memory");
;         }
;     }
;     __syncthreads();
; }
.Lmx_done:
	v_readlane_b32 s0, v255, 26
	s_add_i32 s2, s0, 4
	s_cmp_lt_i32 s2, s83
	s_cselect_b64 s[0:1], -1, 0
	s_and_b64 s[4:5], s[90:91], s[0:1]
	v_readlane_b32 s90, v255, 23
	s_andn2_b64 vcc, exec, s[4:5]
	v_readlane_b32 s56, v255, 21
	v_readlane_b32 s91, v255, 24
	v_readlane_b32 s57, v255, 22
	s_cbranch_vccnz .LBB0_415
	v_readlane_b32 s26, v253, 1
	v_readlane_b32 s27, v253, 2
	s_waitcnt vmcnt(0)
	s_waitcnt vmcnt(0) lgkmcnt(0)
	s_barrier
	v_readlane_b32 s98, v255, 41
	s_cmp_lg_u32 s98, 0
	s_cbranch_scc0 .Lfs4_slow
	v_readlane_b32 s98, v253, 0
	s_cmp_lg_u32 s98, 0
	s_cbranch_scc1 .Lfs4_join
	v_readlane_b32 vcc_lo, v255, 42
	s_and_b32 s98, s66, 7
	s_lshl_b32 s98, s98, 7
	s_add_u32 s98, s98, 0x1783a00
	s_add_u32 s98, s80, s98
	s_addc_u32 s99, s81, 0
	s_add_i32 vcc_lo, vcc_lo, 1
	s_lshr_b32 vcc_hi, s66, 3
	s_lshl_b32 vcc_hi, vcc_hi, 2
	v_writelane_b32 v255, vcc_lo, 42
	v_mbcnt_lo_u32_b32 v5, -1, 0
	v_lshlrev_b32_e32 v5, 2, v5
	v_mov_b32_e32 v6, vcc_lo
	v_mov_b32_e32 v7, vcc_hi
	s_mov_b32 m0, 0
	s_mov_b64 exec, 1
	global_store_dword v7, v6, s[98:99]
	buffer_inv sc1
	s_mov_b32 exec_lo, -1
	s_mov_b32 exec_hi, 0

; __device__ __forceinline__ unsigned xb_ld(unsigned* p)              { return __hip_atomic_load(p, __ATOMIC_RELAXED, __HIP_MEMORY_SCOPE_AGENT); }
; __device__ __forceinline__ unsigned xb_add(unsigned* p, unsigned v) { return __hip_atomic_fetch_add(p, v, __ATOMIC_RELAXED, __HIP_MEMORY_SCOPE_AGENT); }
; #define XB_SPIN(cond, bar) do { unsigned _sp = 0; while (cond) { __builtin_amdgcn_s_sleep(1); \
;     if ((++_sp & 255u) == 0u) { if (xb_ld(&(bar)[XB_TMO])) break; if (_sp > XB_SPIN_CAP) { atomicAdd(&(bar)[XB_TMO], 1u); break; } } } } while (0)
; __device__ __forceinline__ void xcd_barrier(const XcdBarrier& b) {
;     asm volatile("s_waitcnt vmcnt(0)" ::: "memory");
;     __syncthreads();
;     if (threadIdx.x == 0) {
;         unsigned* bar = b.bar;
;         __builtin_amdgcn_s_waitcnt(0);
;         unsigned nloc = b.st[0], nx = b.st[1];
;         if (nloc == 0u) { xcd_barrier_complete(bar, b.x, nloc, nx); b.st[0] = nloc; b.st[1] = nx; }
;         const unsigned old = xb_add(&bar[XB_XSUB(b.x)], 1u);
;         const unsigned gen = old / nloc;
;         if (old + 1u == (gen + 1u) * nloc) {
;             __builtin_amdgcn_fence(__ATOMIC_RELEASE, "agent");
;             asm volatile("s_waitcnt vmcnt(0)" ::: "memory");
;             const unsigned og = xb_add(&bar[XB_TOP], 1u);
;             const unsigned tg = og / nx;
;             if (og + 1u == (tg + 1u) * nx) xb_add(&bar[XB_TOPGEN], 1u);
;             else XB_SPIN(xb_ld(&bar[XB_TOPGEN]) == tg, bar);
;             __builtin_amdgcn_fence(__ATOMIC_ACQUIRE, "agent");
;             xb_add(&bar[XB_XGEN(b.x)], 1u);
;             asm volatile("s_waitcnt vmcnt(0)" ::: "memory");
;         } else {
;             XB_SPIN(xb_ld(&bar[XB_XGEN(b.x)]) == gen, bar);
;             __builtin_amdgcn_fence(__ATOMIC_ACQUIRE, "agent");
;             asm volatile("s_waitcnt vmcnt(0)" ::: "memory");
;         }
;     }
;     __syncthreads();
; }
.Lfs4_join:
	s_mov_b64 s[20:21], exec
	v_readlane_b32 s4, v253, 3
	v_readlane_b32 s5, v253, 4
	s_and_b64 s[4:5], s[20:21], s[4:5]
	s_waitcnt vmcnt(0)
	s_branch .LBB0_414
.Lfs4_slow:
	s_mov_b64 s[20:21], exec
	v_readlane_b32 s4, v253, 3
	v_readlane_b32 s5, v253, 4
	s_and_b64 s[4:5], s[20:21], s[4:5]
	s_mov_b64 exec, s[4:5]
	s_cbranch_execz .LBB0_414
	v_readlane_b32 s4, v255, 11
	s_waitcnt vmcnt(0) expcnt(0) lgkmcnt(0)
	s_nop 0
	v_mov_b32_e32 v4, s4
	ds_read_b32 v6, v4
	v_readlane_b32 s4, v255, 12
	s_waitcnt lgkmcnt(0)
	v_cmp_ne_u32_e32 vcc, 0, v6
	v_mov_b32_e32 v4, s4
	ds_read_b32 v4, v4
	s_cbranch_vccnz .LBB0_385
	s_add_u32 s30, s26, 0x1000
	s_addc_u32 s31, s27, 0
	s_add_u32 s36, s26, 0x1100
	s_addc_u32 s37, s27, 0
	s_add_u32 s38, s26, 0x1200
	s_addc_u32 s39, s27, 0
	s_add_u32 s40, s26, 0x1300
	s_addc_u32 s41, s27, 0
	s_mov_b32 s4, 1
	s_mov_b64 s[42:43], 0
	s_branch .LBB0_375

; __device__ __forceinline__ unsigned xb_ld(unsigned* p)              { return __hip_atomic_load(p, __ATOMIC_RELAXED, __HIP_MEMORY_SCOPE_AGENT); }
; __device__ __forceinline__ unsigned xb_add(unsigned* p, unsigned v) { return __hip_atomic_fetch_add(p, v, __ATOMIC_RELAXED, __HIP_MEMORY_SCOPE_AGENT); }
; #define XB_SPIN(cond, bar) do { unsigned _sp = 0; while (cond) { __builtin_amdgcn_s_sleep(1); \
;     if ((++_sp & 255u) == 0u) { if (xb_ld(&(bar)[XB_TMO])) break; if (_sp > XB_SPIN_CAP) { atomicAdd(&(bar)[XB_TMO], 1u); break; } } } } while (0)
; __device__ __forceinline__ void xcd_barrier(const XcdBarrier& b) {
;     asm volatile("s_waitcnt vmcnt(0)" ::: "memory");
;     __syncthreads();
;     if (threadIdx.x == 0) {
;         unsigned* bar = b.bar;
;         __builtin_amdgcn_s_waitcnt(0);
;         unsigned nloc = b.st[0], nx = b.st[1];
;         if (nloc == 0u) { xcd_barrier_complete(bar, b.x, nloc, nx); b.st[0] = nloc; b.st[1] = nx; }
;         const unsigned old = xb_add(&bar[XB_XSUB(b.x)], 1u);
;         const unsigned gen = old / nloc;
;         if (old + 1u == (gen + 1u) * nloc) {
;             __builtin_amdgcn_fence(__ATOMIC_RELEASE, "agent");
;             asm volatile("s_waitcnt vmcnt(0)" ::: "memory");
;             const unsigned og = xb_add(&bar[XB_TOP], 1u);
;             const unsigned tg = og / nx;
;             if (og + 1u == (tg + 1u) * nx) xb_add(&bar[XB_TOPGEN], 1u);
;             else XB_SPIN(xb_ld(&bar[XB_TOPGEN]) == tg, bar);
;             __builtin_amdgcn_fence(__ATOMIC_ACQUIRE, "agent");
;             xb_add(&bar[XB_XGEN(b.x)], 1u);
;             asm volatile("s_waitcnt vmcnt(0)" ::: "memory");
;         } else {
;             XB_SPIN(xb_ld(&bar[XB_XGEN(b.x)]) == gen, bar);
;             __builtin_amdgcn_fence(__ATOMIC_ACQUIRE, "agent");
;             asm volatile("s_waitcnt vmcnt(0)" ::: "memory");
;         }
;     }
;     __syncthreads();
; }
.Lsw_cont:
	v_readlane_b32 s0, v255, 26
	s_add_i32 s2, s0, 5
	s_cmp_lt_i32 s2, s83
	s_cselect_b64 s[0:1], -1, 0
	s_and_b64 s[4:5], s[26:27], s[0:1]
	s_andn2_b64 vcc, exec, s[4:5]
	s_cbranch_vccnz .LBB0_469
	v_readlane_b32 s26, v253, 1
	v_readlane_b32 s27, v253, 2
	s_waitcnt vmcnt(0)
	s_waitcnt vmcnt(0) lgkmcnt(0)
	s_barrier
	v_readlane_b32 s98, v255, 41
	s_cmp_lg_u32 s98, 0
	s_cbranch_scc0 .Lfs3_slow
	v_readlane_b32 s98, v253, 0
	s_cmp_lg_u32 s98, 0
	s_cbranch_scc1 .Lfs3_join
	v_readlane_b32 vcc_lo, v255, 42
	s_and_b32 s98, s66, 7
	s_lshl_b32 s98, s98, 7
	s_add_u32 s98, s98, 0x1783a00
	s_add_u32 s98, s80, s98
	s_addc_u32 s99, s81, 0
	s_add_i32 vcc_lo, vcc_lo, 1
	s_lshr_b32 vcc_hi, s66, 3
	s_lshl_b32 vcc_hi, vcc_hi, 2
	v_writelane_b32 v255, vcc_lo, 42
	v_mbcnt_lo_u32_b32 v5, -1, 0
	v_lshlrev_b32_e32 v5, 2, v5
	v_mov_b32_e32 v6, vcc_lo
	v_mov_b32_e32 v7, vcc_hi
	s_mov_b32 m0, 0
	s_mov_b64 exec, 1
	global_store_dword v7, v6, s[98:99]
	buffer_inv sc1
	s_mov_b32 exec_lo, -1
	s_mov_b32 exec_hi, 0

; __device__ __forceinline__ unsigned xb_ld(unsigned* p)              { return __hip_atomic_load(p, __ATOMIC_RELAXED, __HIP_MEMORY_SCOPE_AGENT); }
; __device__ __forceinline__ unsigned xb_add(unsigned* p, unsigned v) { return __hip_atomic_fetch_add(p, v, __ATOMIC_RELAXED, __HIP_MEMORY_SCOPE_AGENT); }
; #define XB_SPIN(cond, bar) do { unsigned _sp = 0; while (cond) { __builtin_amdgcn_s_sleep(1); \
;     if ((++_sp & 255u) == 0u) { if (xb_ld(&(bar)[XB_TMO])) break; if (_sp > XB_SPIN_CAP) { atomicAdd(&(bar)[XB_TMO], 1u); break; } } } } while (0)
; __device__ __forceinline__ void xcd_barrier(const XcdBarrier& b) {
;     asm volatile("s_waitcnt vmcnt(0)" ::: "memory");
;     __syncthreads();
;     if (threadIdx.x == 0) {
;         unsigned* bar = b.bar;
;         __builtin_amdgcn_s_waitcnt(0);
;         unsigned nloc = b.st[0], nx = b.st[1];
;         if (nloc == 0u) { xcd_barrier_complete(bar, b.x, nloc, nx); b.st[0] = nloc; b.st[1] = nx; }
;         const unsigned old = xb_add(&bar[XB_XSUB(b.x)], 1u);
;         const unsigned gen = old / nloc;
;         if (old + 1u == (gen + 1u) * nloc) {
;             __builtin_amdgcn_fence(__ATOMIC_RELEASE, "agent");
;             asm volatile("s_waitcnt vmcnt(0)" ::: "memory");
;             const unsigned og = xb_add(&bar[XB_TOP], 1u);
;             const unsigned tg = og / nx;
;             if (og + 1u == (tg + 1u) * nx) xb_add(&bar[XB_TOPGEN], 1u);
;             else XB_SPIN(xb_ld(&bar[XB_TOPGEN]) == tg, bar);
;             __builtin_amdgcn_fence(__ATOMIC_ACQUIRE, "agent");
;             xb_add(&bar[XB_XGEN(b.x)], 1u);
;             asm volatile("s_waitcnt vmcnt(0)" ::: "memory");
;         } else {
;             XB_SPIN(xb_ld(&bar[XB_XGEN(b.x)]) == gen, bar);
;             __builtin_amdgcn_fence(__ATOMIC_ACQUIRE, "agent");
;             asm volatile("s_waitcnt vmcnt(0)" ::: "memory");
;         }
;     }
;     __syncthreads();
; }
.LBB0_524:
	v_readlane_b32 s0, v255, 26
	s_add_i32 s2, s0, 6
	s_cmp_lt_i32 s2, s83
	s_cselect_b64 s[26:27], -1, 0
	s_and_b64 s[0:1], s[20:21], s[26:27]
	s_andn2_b64 vcc, exec, s[0:1]
	s_cbranch_vccnz .LBB0_570
	v_readlane_b32 s20, v253, 1
	v_readlane_b32 s21, v253, 2
	s_waitcnt vmcnt(0)
	s_waitcnt vmcnt(0) lgkmcnt(0)
	s_barrier
	v_readlane_b32 s98, v255, 41
	s_cmp_lg_u32 s98, 0
	s_cbranch_scc0 .Lfs2_slow
	v_readlane_b32 s98, v253, 0
	s_cmp_lg_u32 s98, 0
	s_cbranch_scc1 .Lfs2_join
	v_readlane_b32 vcc_lo, v255, 42
	s_and_b32 s98, s66, 7
	s_lshl_b32 s98, s98, 7
	s_add_u32 s98, s98, 0x1783a00
	s_add_u32 s98, s80, s98
	s_addc_u32 s99, s81, 0
	s_add_i32 vcc_lo, vcc_lo, 1
	s_lshr_b32 vcc_hi, s66, 3
	s_lshl_b32 vcc_hi, vcc_hi, 2
	v_writelane_b32 v255, vcc_lo, 42
	v_mbcnt_lo_u32_b32 v5, -1, 0
	v_lshlrev_b32_e32 v5, 2, v5
	v_mov_b32_e32 v6, vcc_lo
	v_mov_b32_e32 v7, vcc_hi
	s_mov_b32 m0, 0
	s_mov_b64 exec, 1
	global_store_dword v7, v6, s[98:99]
	buffer_inv sc1
	s_mov_b32 exec_lo, -1
	s_mov_b32 exec_hi, 0

; __device__ __forceinline__ unsigned xb_ld(unsigned* p)              { return __hip_atomic_load(p, __ATOMIC_RELAXED, __HIP_MEMORY_SCOPE_AGENT); }
; __device__ __forceinline__ unsigned xb_add(unsigned* p, unsigned v) { return __hip_atomic_fetch_add(p, v, __ATOMIC_RELAXED, __HIP_MEMORY_SCOPE_AGENT); }
; #define XB_SPIN(cond, bar) do { unsigned _sp = 0; while (cond) { __builtin_amdgcn_s_sleep(1); \
;     if ((++_sp & 255u) == 0u) { if (xb_ld(&(bar)[XB_TMO])) break; if (_sp > XB_SPIN_CAP) { atomicAdd(&(bar)[XB_TMO], 1u); break; } } } } while (0)
; __device__ __forceinline__ void xcd_barrier(const XcdBarrier& b) {
;     asm volatile("s_waitcnt vmcnt(0)" ::: "memory");
;     __syncthreads();
;     if (threadIdx.x == 0) {
;         unsigned* bar = b.bar;
;         __builtin_amdgcn_s_waitcnt(0);
;         unsigned nloc = b.st[0], nx = b.st[1];
;         if (nloc == 0u) { xcd_barrier_complete(bar, b.x, nloc, nx); b.st[0] = nloc; b.st[1] = nx; }
;         const unsigned old = xb_add(&bar[XB_XSUB(b.x)], 1u);
;         const unsigned gen = old / nloc;
;         if (old + 1u == (gen + 1u) * nloc) {
;             __builtin_amdgcn_fence(__ATOMIC_RELEASE, "agent");
;             asm volatile("s_waitcnt vmcnt(0)" ::: "memory");
;             const unsigned og = xb_add(&bar[XB_TOP], 1u);
;             const unsigned tg = og / nx;
;             if (og + 1u == (tg + 1u) * nx) xb_add(&bar[XB_TOPGEN], 1u);
;             else XB_SPIN(xb_ld(&bar[XB_TOPGEN]) == tg, bar);
;             __builtin_amdgcn_fence(__ATOMIC_ACQUIRE, "agent");
;             xb_add(&bar[XB_XGEN(b.x)], 1u);
;             asm volatile("s_waitcnt vmcnt(0)" ::: "memory");
;         } else {
;             XB_SPIN(xb_ld(&bar[XB_XGEN(b.x)]) == gen, bar);
;             __builtin_amdgcn_fence(__ATOMIC_ACQUIRE, "agent");
;             asm volatile("s_waitcnt vmcnt(0)" ::: "memory");
;         }
;     }
;     __syncthreads();
; }
.Lfs2_slow:
	s_mov_b64 s[0:1], exec
	v_readlane_b32 s4, v253, 3
	v_readlane_b32 s5, v253, 4
	s_and_b64 s[4:5], s[0:1], s[4:5]
	s_mov_b64 exec, s[4:5]
	s_cbranch_execz .LBB0_569
	v_readlane_b32 s4, v255, 11
	s_waitcnt vmcnt(0) expcnt(0) lgkmcnt(0)
	s_nop 0
	v_mov_b32_e32 v4, s4
	ds_read_b32 v6, v4
	v_readlane_b32 s4, v255, 12
	s_waitcnt lgkmcnt(0)
	v_cmp_ne_u32_e32 vcc, 0, v6
	v_mov_b32_e32 v4, s4
	ds_read_b32 v4, v4
	s_cbranch_vccnz .LBB0_540
	s_add_u32 s30, s20, 0x1000
	s_addc_u32 s31, s21, 0
	s_add_u32 s36, s20, 0x1100
	s_addc_u32 s37, s21, 0
	s_add_u32 s38, s20, 0x1200
	s_addc_u32 s39, s21, 0
	s_add_u32 s40, s20, 0x1300
	s_addc_u32 s41, s21, 0
	s_mov_b32 s4, 1
	s_mov_b64 s[42:43], 0
	s_branch .LBB0_530

; __device__ __forceinline__ unsigned xb_ld(unsigned* p)              { return __hip_atomic_load(p, __ATOMIC_RELAXED, __HIP_MEMORY_SCOPE_AGENT); }
; __device__ __forceinline__ unsigned xb_add(unsigned* p, unsigned v) { return __hip_atomic_fetch_add(p, v, __ATOMIC_RELAXED, __HIP_MEMORY_SCOPE_AGENT); }
; #define XB_SPIN(cond, bar) do { unsigned _sp = 0; while (cond) { __builtin_amdgcn_s_sleep(1); \
;     if ((++_sp & 255u) == 0u) { if (xb_ld(&(bar)[XB_TMO])) break; if (_sp > XB_SPIN_CAP) { atomicAdd(&(bar)[XB_TMO], 1u); break; } } } } while (0)
; __device__ __forceinline__ void xcd_barrier(const XcdBarrier& b) {
;     asm volatile("s_waitcnt vmcnt(0)" ::: "memory");
;     __syncthreads();
;     if (threadIdx.x == 0) {
;         unsigned* bar = b.bar;
;         __builtin_amdgcn_s_waitcnt(0);
;         unsigned nloc = b.st[0], nx = b.st[1];
;         if (nloc == 0u) { xcd_barrier_complete(bar, b.x, nloc, nx); b.st[0] = nloc; b.st[1] = nx; }
;         const unsigned old = xb_add(&bar[XB_XSUB(b.x)], 1u);
;         const unsigned gen = old / nloc;
;         if (old + 1u == (gen + 1u) * nloc) {
;             __builtin_amdgcn_fence(__ATOMIC_RELEASE, "agent");
;             asm volatile("s_waitcnt vmcnt(0)" ::: "memory");
;             const unsigned og = xb_add(&bar[XB_TOP], 1u);
;             const unsigned tg = og / nx;
;             if (og + 1u == (tg + 1u) * nx) xb_add(&bar[XB_TOPGEN], 1u);
;             else XB_SPIN(xb_ld(&bar[XB_TOPGEN]) == tg, bar);
;             __builtin_amdgcn_fence(__ATOMIC_ACQUIRE, "agent");
;             xb_add(&bar[XB_XGEN(b.x)], 1u);
;             asm volatile("s_waitcnt vmcnt(0)" ::: "memory");
;         } else {
;             XB_SPIN(xb_ld(&bar[XB_XGEN(b.x)]) == gen, bar);
;             __builtin_amdgcn_fence(__ATOMIC_ACQUIRE, "agent");
;             asm volatile("s_waitcnt vmcnt(0)" ::: "memory");
;         }
;     }
;     __syncthreads();
; }
.LBB0_702:
	v_readlane_b32 s18, v253, 1
	v_readlane_b32 s19, v253, 2
	s_waitcnt vmcnt(0)
	s_waitcnt vmcnt(0) lgkmcnt(0)
	s_barrier
	v_readlane_b32 s98, v255, 41
	s_cmp_lg_u32 s98, 0
	s_cbranch_scc0 .Lfs1_slow
	v_readlane_b32 s98, v253, 0
	s_cmp_lg_u32 s98, 0
	s_cbranch_scc1 .Lfs1_join
	v_readlane_b32 vcc_lo, v255, 42
	s_and_b32 s98, s66, 7
	s_lshl_b32 s98, s98, 7
	s_add_u32 s98, s98, 0x1783a00
	s_add_u32 s98, s80, s98
	s_addc_u32 s99, s81, 0
	s_add_i32 vcc_lo, vcc_lo, 1
	s_lshr_b32 vcc_hi, s66, 3
	s_lshl_b32 vcc_hi, vcc_hi, 2
	v_writelane_b32 v255, vcc_lo, 42
	v_mbcnt_lo_u32_b32 v5, -1, 0
	v_lshlrev_b32_e32 v5, 2, v5
	v_mov_b32_e32 v6, vcc_lo
	v_mov_b32_e32 v7, vcc_hi
	s_mov_b32 m0, 0
	s_mov_b64 exec, 1
	global_store_dword v7, v6, s[98:99]
	buffer_inv sc1
	s_mov_b32 exec_lo, -1
	s_mov_b32 exec_hi, 0

; __device__ __forceinline__ unsigned xb_ld(unsigned* p)              { return __hip_atomic_load(p, __ATOMIC_RELAXED, __HIP_MEMORY_SCOPE_AGENT); }
; __device__ __forceinline__ unsigned xb_add(unsigned* p, unsigned v) { return __hip_atomic_fetch_add(p, v, __ATOMIC_RELAXED, __HIP_MEMORY_SCOPE_AGENT); }
; #define XB_SPIN(cond, bar) do { unsigned _sp = 0; while (cond) { __builtin_amdgcn_s_sleep(1); \
;     if ((++_sp & 255u) == 0u) { if (xb_ld(&(bar)[XB_TMO])) break; if (_sp > XB_SPIN_CAP) { atomicAdd(&(bar)[XB_TMO], 1u); break; } } } } while (0)
; __device__ __forceinline__ void xcd_barrier(const XcdBarrier& b) {
;     asm volatile("s_waitcnt vmcnt(0)" ::: "memory");
;     __syncthreads();
;     if (threadIdx.x == 0) {
;         unsigned* bar = b.bar;
;         __builtin_amdgcn_s_waitcnt(0);
;         unsigned nloc = b.st[0], nx = b.st[1];
;         if (nloc == 0u) { xcd_barrier_complete(bar, b.x, nloc, nx); b.st[0] = nloc; b.st[1] = nx; }
;         const unsigned old = xb_add(&bar[XB_XSUB(b.x)], 1u);
;         const unsigned gen = old / nloc;
;         if (old + 1u == (gen + 1u) * nloc) {
;             __builtin_amdgcn_fence(__ATOMIC_RELEASE, "agent");
;             asm volatile("s_waitcnt vmcnt(0)" ::: "memory");
;             const unsigned og = xb_add(&bar[XB_TOP], 1u);
;             const unsigned tg = og / nx;
;             if (og + 1u == (tg + 1u) * nx) xb_add(&bar[XB_TOPGEN], 1u);
;             else XB_SPIN(xb_ld(&bar[XB_TOPGEN]) == tg, bar);
;             __builtin_amdgcn_fence(__ATOMIC_ACQUIRE, "agent");
;             xb_add(&bar[XB_XGEN(b.x)], 1u);
;             asm volatile("s_waitcnt vmcnt(0)" ::: "memory");
;         } else {
;             XB_SPIN(xb_ld(&bar[XB_XGEN(b.x)]) == gen, bar);
;             __builtin_amdgcn_fence(__ATOMIC_ACQUIRE, "agent");
;             asm volatile("s_waitcnt vmcnt(0)" ::: "memory");
;         }
;     }
;     __syncthreads();
; }
.Lfs1_slow:
	s_mov_b64 s[0:1], exec
	v_readlane_b32 s4, v253, 3
	v_readlane_b32 s5, v253, 4
	s_and_b64 s[4:5], s[0:1], s[4:5]
	s_mov_b64 exec, s[4:5]
	s_cbranch_execnz .LBB0_703
	s_getpc_b64 s[98:99]
